# k23
# baseline (speedup 1.0000x reference)
; template <int EPI>
; __device__ __forceinline__ void gemm_phase(const GemmDesc d, u16* shm, unsigned sx, unsigned srank, unsigned snloc) {
;     ...
;         const int b = pn >> 4, s0 = (pn & 15) * 128;
;         const float sgn = (pm == 0) ? 1.f : -1.f;
;         float rs0[2], rs1[2];
; #pragma unroll
;         for (int n = 0; n < 2; ++n) { rs0[n] = lr[wc2 * 32 + n * 16 + fr2]; rs1[n] = sgn * lr[128 + wc2 * 32 + n * 16 + fr2]; }
;         u16* outp = d.outb + ((size_t)b * 1024 + z * 256) * 4096 + (size_t)pm * 2048 + s0 + wc2 * 32 + c4;
; #pragma unroll
;         for (int ai = 0; ai < 2; ++ai)
; #pragma unroll
;           for (int m = 0; m < 4; ++m) {
; #pragma unroll
;             for (int j = 0; j < 4; ++j) {
;               const float v0 = acc[ai][0][m][0][j] * rs0[0] + acc[ai][1][m][0][j] * rs1[0];
;               const float v1 = acc[ai][0][m][1][j] * rs0[1] + acc[ai][1][m][1][j] * rs1[1];
;               stg[(fq2 * 4 + j) * 36 + fr2] = v0; stg[(fq2 * 4 + j) * 36 + 16 + fr2] = v1;
;               if (pm == 0) {
;                 float a = (fr2 & 1) ? -(v0 + v1) : (v0 + v1);
;                 a += __shfl_xor(a, 1); a += __shfl_xor(a, 2); a += __shfl_xor(a, 4); a += __shfl_xor(a, 8);
;                 if (fr2 == 0) d.xs[((size_t)((pn & 15) * 4 + wc2)) * (NBATCH * DM) + (size_t)b * DM + z * 256 + ai * 128 + wr2 * 64 + m * 16 + fq2 * 4 + j] = a;
;               }
.LBB0_212:
	s_or_b64 exec, exec, s[4:5]
	v_ashrrev_i32_e32 v132, 6, v149
	s_movk_i32 s4, 0x900
	v_mul_lo_u32 v135, v132, s4
	s_lshl_b32 s4, s6, 8
	s_and_b32 s28, s4, 0x100
	s_lshl_b32 s4, s28, 2
	v_and_b32_e32 v153, 3, v132
	v_and_b32_e32 v134, 15, v149
	s_add_i32 s4, s4, 0
	s_add_i32 s4, s4, 0x20000
	v_lshlrev_b32_e32 v132, 7, v153
	v_lshlrev_b32_e32 v155, 2, v134
	v_add3_u32 v136, s4, v132, v155
	s_and_b32 s20, s85, 15
	ds_read2_b32 v[132:133], v136 offset0:128 offset1:144
	s_cmp_eq_u32 s84, 0
	s_cselect_b64 s[22:23], -1, 0
	s_ashr_i32 s18, s85, 4
	s_ashr_i32 s19, s18, 31
	s_lshl_b32 s4, s96, 8
	s_ashr_i32 s5, s4, 31
	s_lshl_b64 s[12:13], s[18:19], 12
	s_add_u32 s16, s1, s12
	s_waitcnt lgkmcnt(0)
	v_cndmask_b32_e64 v152, -v132, v132, s[22:23]
	v_lshrrev_b32_e32 v132, 2, v149
	s_addc_u32 s17, s57, s13
	s_lshl_b32 s21, s20, 17
	v_and_b32_e32 v156, 12, v132
	v_and_b32_e32 v132, 1, v149
	ds_read2_b32 v[136:137], v136 offset1:16
	v_cmp_eq_u32_e64 s[14:15], 0, v132
	v_ashrrev_i32_e32 v132, 2, v149
	v_lshl_or_b32 v176, v153, 15, s21
	v_add_u32_e32 v154, s83, v135
	v_cmp_eq_u32_e64 s[12:13], 0, v134
	v_and_b32_e32 v132, 0xffffffc0, v132
	v_lshl_add_u64 v[134:135], s[16:17], 0, v[176:177]
	v_cndmask_b32_e64 v151, -v133, v133, s[22:23]
	v_ashrrev_i32_e32 v133, 31, v132
	v_lshl_add_u64 v[134:135], s[4:5], 2, v[134:135]
	v_lshl_add_u64 v[134:135], v[132:133], 2, v[134:135]
	v_mul_f32_e32 v133, v116, v152
	v_mul_u32_u24_e32 v116, 36, v156
	v_lshlrev_b32_e32 v176, 2, v156
	v_mul_f32_e32 v112, v112, v151
	v_lshlrev_b32_e32 v116, 2, v116
	s_cmp_lg_u32 s84, 0
	v_lshl_add_u64 v[134:135], v[134:135], 0, v[176:177]
	s_waitcnt lgkmcnt(0)
	v_fmac_f32_e32 v133, v124, v136
	v_fmac_f32_e32 v112, v120, v137
	v_add3_u32 v120, v154, v155, v116
	v_add3_u32 v116, v154, v116, v155
	s_mov_b32 s31, 0x800000
	v_readlane_b32 s52, v239, 23
	ds_write_b32 v120, v133
	ds_write_b32 v116, v112 offset:64
	s_cbranch_scc1 .LBB0_216
	v_add_f32_e32 v112, v133, v112
	v_cndmask_b32_e64 v112, -v112, v112, s[14:15]
	s_nop 1
	v_add_f32_dpp v112, v112, v112 quad_perm:[1,0,3,2] row_mask:0xf bank_mask:0xf
	s_nop 1
	v_add_f32_dpp v112, v112, v112 quad_perm:[2,3,0,1] row_mask:0xf bank_mask:0xf
	s_nop 1
	v_add_f32_dpp v112, v112, v112 row_half_mirror row_mask:0xf bank_mask:0xf
	s_nop 1
	v_add_f32_dpp v112, v112, v112 row_mirror row_mask:0xf bank_mask:0xf
	s_and_saveexec_b64 s[16:17], s[12:13]
	s_cbranch_execz .LBB0_215
	s_waitcnt lgkmcnt(0)
	global_store_dword v[134:135], v112, off

; template <int EPI>
; __device__ __forceinline__ void gemm_phase(const GemmDesc d, u16* shm, unsigned sx, unsigned srank, unsigned snloc) {
;     ...
;             for (int j = 0; j < 4; ++j) {
;               const float v0 = acc[ai][0][m][0][j] * rs0[0] + acc[ai][1][m][0][j] * rs1[0];
;               const float v1 = acc[ai][0][m][1][j] * rs0[1] + acc[ai][1][m][1][j] * rs1[1];
;               stg[(fq2 * 4 + j) * 36 + fr2] = v0; stg[(fq2 * 4 + j) * 36 + 16 + fr2] = v1;
;               if (pm == 0) {
;                 float a = (fr2 & 1) ? -(v0 + v1) : (v0 + v1);
;                 a += __shfl_xor(a, 1); a += __shfl_xor(a, 2); a += __shfl_xor(a, 4); a += __shfl_xor(a, 8);
;                 if (fr2 == 0) d.xs[((size_t)((pn & 15) * 4 + wc2)) * (NBATCH * DM) + (size_t)b * DM + z * 256 + ai * 128 + wr2 * 64 + m * 16 + fq2 * 4 + j] = a;
;               }
.LBB0_216:
	v_mul_f32_e32 v112, v117, v152
	v_mul_f32_e32 v113, v113, v151
	v_cndmask_b32_e64 v117, 0, 1, s[22:23]
	v_fmac_f32_e32 v112, v125, v136
	v_fmac_f32_e32 v113, v121, v137
	v_cmp_ne_u32_e64 s[16:17], 1, v117
	s_andn2_b64 vcc, exec, s[22:23]
	ds_write_b32 v120, v112 offset:144
	ds_write_b32 v116, v113 offset:208
	s_cbranch_vccnz .LBB0_220
	v_add_f32_e32 v112, v112, v113
	v_cndmask_b32_e64 v112, -v112, v112, s[14:15]
	s_nop 1
	v_add_f32_dpp v112, v112, v112 quad_perm:[1,0,3,2] row_mask:0xf bank_mask:0xf
	s_nop 1
	v_add_f32_dpp v112, v112, v112 quad_perm:[2,3,0,1] row_mask:0xf bank_mask:0xf
	s_nop 1
	v_add_f32_dpp v112, v112, v112 row_half_mirror row_mask:0xf bank_mask:0xf
	s_nop 1
	v_add_f32_dpp v112, v112, v112 row_mirror row_mask:0xf bank_mask:0xf
	s_and_saveexec_b64 s[22:23], s[12:13]
	s_cbranch_execz .LBB0_219
	s_waitcnt lgkmcnt(0)
	global_store_dword v[134:135], v112, off offset:4

; template <int EPI>
; __device__ __forceinline__ void gemm_phase(const GemmDesc d, u16* shm, unsigned sx, unsigned srank, unsigned snloc) {
;     ...
;             for (int j = 0; j < 4; ++j) {
;               const float v0 = acc[ai][0][m][0][j] * rs0[0] + acc[ai][1][m][0][j] * rs1[0];
;               const float v1 = acc[ai][0][m][1][j] * rs0[1] + acc[ai][1][m][1][j] * rs1[1];
;               stg[(fq2 * 4 + j) * 36 + fr2] = v0; stg[(fq2 * 4 + j) * 36 + 16 + fr2] = v1;
;               if (pm == 0) {
;                 float a = (fr2 & 1) ? -(v0 + v1) : (v0 + v1);
;                 a += __shfl_xor(a, 1); a += __shfl_xor(a, 2); a += __shfl_xor(a, 4); a += __shfl_xor(a, 8);
;                 if (fr2 == 0) d.xs[((size_t)((pn & 15) * 4 + wc2)) * (NBATCH * DM) + (size_t)b * DM + z * 256 + ai * 128 + wr2 * 64 + m * 16 + fq2 * 4 + j] = a;
;               }
.LBB0_220:
	v_mul_f32_e32 v112, v118, v152
	s_waitcnt lgkmcnt(0)
	v_mul_f32_e32 v113, v114, v151
	v_fmac_f32_e32 v112, v126, v136
	v_fmac_f32_e32 v113, v122, v137
	s_and_b64 vcc, exec, s[16:17]
	ds_write_b32 v120, v112 offset:288
	ds_write_b32 v116, v113 offset:352
	s_cbranch_vccnz .LBB0_224
	v_add_f32_e32 v112, v112, v113
	v_cndmask_b32_e64 v112, -v112, v112, s[14:15]
	s_nop 1
	v_add_f32_dpp v112, v112, v112 quad_perm:[1,0,3,2] row_mask:0xf bank_mask:0xf
	s_nop 1
	v_add_f32_dpp v112, v112, v112 quad_perm:[2,3,0,1] row_mask:0xf bank_mask:0xf
	s_nop 1
	v_add_f32_dpp v112, v112, v112 row_half_mirror row_mask:0xf bank_mask:0xf
	s_nop 1
	v_add_f32_dpp v112, v112, v112 row_mirror row_mask:0xf bank_mask:0xf
	s_and_saveexec_b64 s[22:23], s[12:13]
	s_cbranch_execz .LBB0_223
	s_waitcnt lgkmcnt(0)
	global_store_dword v[134:135], v112, off offset:8

; template <int EPI>
; __device__ __forceinline__ void gemm_phase(const GemmDesc d, u16* shm, unsigned sx, unsigned srank, unsigned snloc) {
;     ...
;             for (int j = 0; j < 4; ++j) {
;               const float v0 = acc[ai][0][m][0][j] * rs0[0] + acc[ai][1][m][0][j] * rs1[0];
;               const float v1 = acc[ai][0][m][1][j] * rs0[1] + acc[ai][1][m][1][j] * rs1[1];
;               stg[(fq2 * 4 + j) * 36 + fr2] = v0; stg[(fq2 * 4 + j) * 36 + 16 + fr2] = v1;
;               if (pm == 0) {
;                 float a = (fr2 & 1) ? -(v0 + v1) : (v0 + v1);
;                 a += __shfl_xor(a, 1); a += __shfl_xor(a, 2); a += __shfl_xor(a, 4); a += __shfl_xor(a, 8);
;                 if (fr2 == 0) d.xs[((size_t)((pn & 15) * 4 + wc2)) * (NBATCH * DM) + (size_t)b * DM + z * 256 + ai * 128 + wr2 * 64 + m * 16 + fq2 * 4 + j] = a;
;               }
.LBB0_224:
	v_mul_f32_e32 v112, v119, v152
	s_waitcnt lgkmcnt(0)
	v_mul_f32_e32 v113, v115, v151
	v_fmac_f32_e32 v112, v127, v136
	v_fmac_f32_e32 v113, v123, v137
	s_and_b64 vcc, exec, s[16:17]
	ds_write_b32 v120, v112 offset:432
	ds_write_b32 v116, v113 offset:496
	s_cbranch_vccnz .LBB0_228
	v_add_f32_e32 v112, v112, v113
	v_cndmask_b32_e64 v112, -v112, v112, s[14:15]
	s_nop 1
	v_add_f32_dpp v112, v112, v112 quad_perm:[1,0,3,2] row_mask:0xf bank_mask:0xf
	s_nop 1
	v_add_f32_dpp v112, v112, v112 quad_perm:[2,3,0,1] row_mask:0xf bank_mask:0xf
	s_nop 1
	v_add_f32_dpp v112, v112, v112 row_half_mirror row_mask:0xf bank_mask:0xf
	s_nop 1
	v_add_f32_dpp v112, v112, v112 row_mirror row_mask:0xf bank_mask:0xf
	s_and_saveexec_b64 s[22:23], s[12:13]
	s_cbranch_execz .LBB0_227
	s_waitcnt lgkmcnt(0)
	global_store_dword v[134:135], v112, off offset:12

; __device__ __forceinline__ unsigned pack2(float lo, float hi) { unsigned r; asm volatile("v_cvt_pk_bf16_f32 %0, %1, %2" : "=v"(r) : "v"(lo), "v"(hi)); return r; }
; template <int EPI>
; __device__ __forceinline__ void gemm_phase(const GemmDesc d, u16* shm, unsigned sx, unsigned srank, unsigned snloc) {
;     ...
;         u16* outp = d.outb + ((size_t)b * 1024 + z * 256) * 4096 + (size_t)pm * 2048 + s0 + wc2 * 32 + c4;
; #pragma unroll
;         for (int ai = 0; ai < 2; ++ai)
; #pragma unroll
;           for (int m = 0; m < 4; ++m) {
; #pragma unroll
;             for (int j = 0; j < 4; ++j) {
;               const float v0 = acc[ai][0][m][0][j] * rs0[0] + acc[ai][1][m][0][j] * rs1[0];
;               const float v1 = acc[ai][0][m][1][j] * rs0[1] + acc[ai][1][m][1][j] * rs1[1];
;               stg[(fq2 * 4 + j) * 36 + fr2] = v0; stg[(fq2 * 4 + j) * 36 + 16 + fr2] = v1;
;               if (pm == 0) {
;                 float a = (fr2 & 1) ? -(v0 + v1) : (v0 + v1);
;                 a += __shfl_xor(a, 1); a += __shfl_xor(a, 2); a += __shfl_xor(a, 4); a += __shfl_xor(a, 8);
;                 if (fr2 == 0) d.xs[((size_t)((pn & 15) * 4 + wc2)) * (NBATCH * DM) + (size_t)b * DM + z * 256 + ai * 128 + wr2 * 64 + m * 16 + fq2 * 4 + j] = a;
;               }
;             }
; #pragma unroll
;             for (int i = 0; i < 2; ++i) {
;               const int row_l = i * 8 + rl;
;               f32x4 v = *(const f32x4*)&stg[row_l * 36 + c4];
;               u32x2 w = {pack2(v[0], v[1]), pack2(v[2], v[3])};
;               *(u32x2*)(outp + (size_t)(ai * 128 + wr2 * 64 + m * 16 + row_l) * 4096) = w;
;             }
.LBB0_228:
	s_lshl_b64 s[18:19], s[18:19], 10
	s_add_u32 s4, s18, s4
	s_addc_u32 s5, s19, s5
	s_lshl_b64 s[4:5], s[4:5], 13
	s_add_u32 s4, s24, s4
	s_addc_u32 s5, s25, s5
	s_lshl_b32 s18, s84, 12
	s_add_u32 s4, s4, s18
	s_addc_u32 s5, s5, 0
	s_lshl_b32 s18, s20, 8
	v_lshlrev_b32_e32 v112, 2, v149
	s_add_u32 s4, s4, s18
	v_and_b32_e32 v115, 28, v112
	s_addc_u32 s5, s5, 0
	v_lshlrev_b32_e32 v176, 6, v153
	v_bfe_u32 v114, v149, 3, 3
	s_waitcnt lgkmcnt(0)
	v_lshl_add_u64 v[112:113], s[4:5], 0, v[176:177]
	v_lshl_add_u32 v117, v115, 2, v154
	s_movk_i32 s4, 0x90
	v_mad_u32_u24 v121, v114, s4, v117
	ds_read_b128 v[122:125], v121
	s_waitcnt lgkmcnt(0)
	v_cvt_pk_bf16_f32 v118, v122, v123
	v_or_b32_e32 v122, v114, v132
	v_lshlrev_b32_e32 v176, 1, v115
	v_ashrrev_i32_e32 v123, 31, v122
	v_lshl_add_u64 v[112:113], v[112:113], 0, v[176:177]
	v_lshlrev_b64 v[122:123], 13, v[122:123]
	v_lshl_add_u64 v[122:123], v[112:113], 0, v[122:123]
	v_cvt_pk_bf16_f32 v119, v124, v125
	global_store_dwordx2 v[122:123], v[118:119], off
	v_or_b32_e32 v115, 8, v114
	ds_read_b128 v[122:125], v121 offset:1152
	s_waitcnt lgkmcnt(0)
	v_cvt_pk_bf16_f32 v118, v122, v123
	v_or_b32_e32 v122, v115, v132
	v_ashrrev_i32_e32 v123, 31, v122
	v_lshlrev_b64 v[122:123], 13, v[122:123]
	v_mul_f32_e32 v100, v100, v152
	v_mul_f32_e32 v96, v96, v151
	v_lshl_add_u64 v[122:123], v[112:113], 0, v[122:123]
	v_fmac_f32_e32 v100, v108, v136
	v_fmac_f32_e32 v96, v104, v137
	s_and_b64 vcc, exec, s[16:17]
	v_cvt_pk_bf16_f32 v119, v124, v125
	global_store_dwordx2 v[122:123], v[118:119], off
	ds_write_b32 v120, v100
	ds_write_b32 v116, v96 offset:64
	s_cbranch_vccnz .LBB0_232
	v_add_f32_e32 v96, v100, v96
	v_cndmask_b32_e64 v96, -v96, v96, s[14:15]
	s_nop 1
	v_add_f32_dpp v96, v96, v96 quad_perm:[1,0,3,2] row_mask:0xf bank_mask:0xf
	s_nop 1
	v_add_f32_dpp v96, v96, v96 quad_perm:[2,3,0,1] row_mask:0xf bank_mask:0xf
	s_nop 1
	v_add_f32_dpp v96, v96, v96 row_half_mirror row_mask:0xf bank_mask:0xf
	s_nop 1
	v_add_f32_dpp v96, v96, v96 row_mirror row_mask:0xf bank_mask:0xf
	s_and_saveexec_b64 s[4:5], s[12:13]
	s_cbranch_execz .LBB0_231
	s_waitcnt lgkmcnt(0)
	global_store_dword v[134:135], v96, off offset:64

; template <int EPI>
; __device__ __forceinline__ void gemm_phase(const GemmDesc d, u16* shm, unsigned sx, unsigned srank, unsigned snloc) {
;     ...
;             for (int j = 0; j < 4; ++j) {
;               const float v0 = acc[ai][0][m][0][j] * rs0[0] + acc[ai][1][m][0][j] * rs1[0];
;               const float v1 = acc[ai][0][m][1][j] * rs0[1] + acc[ai][1][m][1][j] * rs1[1];
;               stg[(fq2 * 4 + j) * 36 + fr2] = v0; stg[(fq2 * 4 + j) * 36 + 16 + fr2] = v1;
;               if (pm == 0) {
;                 float a = (fr2 & 1) ? -(v0 + v1) : (v0 + v1);
;                 a += __shfl_xor(a, 1); a += __shfl_xor(a, 2); a += __shfl_xor(a, 4); a += __shfl_xor(a, 8);
;                 if (fr2 == 0) d.xs[((size_t)((pn & 15) * 4 + wc2)) * (NBATCH * DM) + (size_t)b * DM + z * 256 + ai * 128 + wr2 * 64 + m * 16 + fq2 * 4 + j] = a;
;               }
.LBB0_232:
	v_mul_f32_e32 v96, v101, v152
	v_mul_f32_e32 v97, v97, v151
	v_fmac_f32_e32 v96, v109, v136
	v_fmac_f32_e32 v97, v105, v137
	s_and_b64 vcc, exec, s[16:17]
	ds_write_b32 v120, v96 offset:144
	ds_write_b32 v116, v97 offset:208
	s_cbranch_vccnz .LBB0_236
	s_waitcnt lgkmcnt(2)
	v_add_f32_e32 v96, v96, v97
	v_cndmask_b32_e64 v96, -v96, v96, s[14:15]
	s_nop 1
	v_add_f32_dpp v96, v96, v96 quad_perm:[1,0,3,2] row_mask:0xf bank_mask:0xf
	s_nop 1
	v_add_f32_dpp v96, v96, v96 quad_perm:[2,3,0,1] row_mask:0xf bank_mask:0xf
	s_nop 1
	v_add_f32_dpp v96, v96, v96 row_half_mirror row_mask:0xf bank_mask:0xf
	s_nop 1
	v_add_f32_dpp v96, v96, v96 row_mirror row_mask:0xf bank_mask:0xf
	s_and_saveexec_b64 s[4:5], s[12:13]
	s_cbranch_execz .LBB0_235
	s_waitcnt lgkmcnt(0)
	global_store_dword v[134:135], v96, off offset:68

; template <int EPI>
; __device__ __forceinline__ void gemm_phase(const GemmDesc d, u16* shm, unsigned sx, unsigned srank, unsigned snloc) {
;     ...
;             for (int j = 0; j < 4; ++j) {
;               const float v0 = acc[ai][0][m][0][j] * rs0[0] + acc[ai][1][m][0][j] * rs1[0];
;               const float v1 = acc[ai][0][m][1][j] * rs0[1] + acc[ai][1][m][1][j] * rs1[1];
;               stg[(fq2 * 4 + j) * 36 + fr2] = v0; stg[(fq2 * 4 + j) * 36 + 16 + fr2] = v1;
;               if (pm == 0) {
;                 float a = (fr2 & 1) ? -(v0 + v1) : (v0 + v1);
;                 a += __shfl_xor(a, 1); a += __shfl_xor(a, 2); a += __shfl_xor(a, 4); a += __shfl_xor(a, 8);
;                 if (fr2 == 0) d.xs[((size_t)((pn & 15) * 4 + wc2)) * (NBATCH * DM) + (size_t)b * DM + z * 256 + ai * 128 + wr2 * 64 + m * 16 + fq2 * 4 + j] = a;
;               }
.LBB0_236:
	v_mul_f32_e32 v96, v102, v152
	s_waitcnt lgkmcnt(0)
	v_mul_f32_e32 v97, v98, v151
	v_fmac_f32_e32 v96, v110, v136
	v_fmac_f32_e32 v97, v106, v137
	s_and_b64 vcc, exec, s[16:17]
	ds_write_b32 v120, v96 offset:288
	ds_write_b32 v116, v97 offset:352
	s_cbranch_vccnz .LBB0_240
	v_add_f32_e32 v96, v96, v97
	v_cndmask_b32_e64 v96, -v96, v96, s[14:15]
	s_nop 1
	v_add_f32_dpp v96, v96, v96 quad_perm:[1,0,3,2] row_mask:0xf bank_mask:0xf
	s_nop 1
	v_add_f32_dpp v96, v96, v96 quad_perm:[2,3,0,1] row_mask:0xf bank_mask:0xf
	s_nop 1
	v_add_f32_dpp v96, v96, v96 row_half_mirror row_mask:0xf bank_mask:0xf
	s_nop 1
	v_add_f32_dpp v96, v96, v96 row_mirror row_mask:0xf bank_mask:0xf
	s_and_saveexec_b64 s[4:5], s[12:13]
	s_cbranch_execz .LBB0_239
	s_waitcnt lgkmcnt(0)
	global_store_dword v[134:135], v96, off offset:72

; template <int EPI>
; __device__ __forceinline__ void gemm_phase(const GemmDesc d, u16* shm, unsigned sx, unsigned srank, unsigned snloc) {
;     ...
;             for (int j = 0; j < 4; ++j) {
;               const float v0 = acc[ai][0][m][0][j] * rs0[0] + acc[ai][1][m][0][j] * rs1[0];
;               const float v1 = acc[ai][0][m][1][j] * rs0[1] + acc[ai][1][m][1][j] * rs1[1];
;               stg[(fq2 * 4 + j) * 36 + fr2] = v0; stg[(fq2 * 4 + j) * 36 + 16 + fr2] = v1;
;               if (pm == 0) {
;                 float a = (fr2 & 1) ? -(v0 + v1) : (v0 + v1);
;                 a += __shfl_xor(a, 1); a += __shfl_xor(a, 2); a += __shfl_xor(a, 4); a += __shfl_xor(a, 8);
;                 if (fr2 == 0) d.xs[((size_t)((pn & 15) * 4 + wc2)) * (NBATCH * DM) + (size_t)b * DM + z * 256 + ai * 128 + wr2 * 64 + m * 16 + fq2 * 4 + j] = a;
;               }
.LBB0_240:
	v_mul_f32_e32 v96, v103, v152
	s_waitcnt lgkmcnt(0)
	v_mul_f32_e32 v97, v99, v151
	v_fmac_f32_e32 v96, v111, v136
	v_fmac_f32_e32 v97, v107, v137
	s_and_b64 vcc, exec, s[16:17]
	ds_write_b32 v120, v96 offset:432
	ds_write_b32 v116, v97 offset:496
	s_cbranch_vccnz .LBB0_244
	v_add_f32_e32 v96, v96, v97
	v_cndmask_b32_e64 v96, -v96, v96, s[14:15]
	s_nop 1
	v_add_f32_dpp v96, v96, v96 quad_perm:[1,0,3,2] row_mask:0xf bank_mask:0xf
	s_nop 1
	v_add_f32_dpp v96, v96, v96 quad_perm:[2,3,0,1] row_mask:0xf bank_mask:0xf
	s_nop 1
	v_add_f32_dpp v96, v96, v96 row_half_mirror row_mask:0xf bank_mask:0xf
	s_nop 1
	v_add_f32_dpp v96, v96, v96 row_mirror row_mask:0xf bank_mask:0xf
	s_and_saveexec_b64 s[4:5], s[12:13]
	s_cbranch_execz .LBB0_243
	s_waitcnt lgkmcnt(0)
	global_store_dword v[134:135], v96, off offset:76

; __device__ __forceinline__ unsigned pack2(float lo, float hi) { unsigned r; asm volatile("v_cvt_pk_bf16_f32 %0, %1, %2" : "=v"(r) : "v"(lo), "v"(hi)); return r; }
; template <int EPI>
; __device__ __forceinline__ void gemm_phase(const GemmDesc d, u16* shm, unsigned sx, unsigned srank, unsigned snloc) {
;     ...
;               const float v0 = acc[ai][0][m][0][j] * rs0[0] + acc[ai][1][m][0][j] * rs1[0];
;               const float v1 = acc[ai][0][m][1][j] * rs0[1] + acc[ai][1][m][1][j] * rs1[1];
;               stg[(fq2 * 4 + j) * 36 + fr2] = v0; stg[(fq2 * 4 + j) * 36 + 16 + fr2] = v1;
;               if (pm == 0) {
;                 float a = (fr2 & 1) ? -(v0 + v1) : (v0 + v1);
;                 a += __shfl_xor(a, 1); a += __shfl_xor(a, 2); a += __shfl_xor(a, 4); a += __shfl_xor(a, 8);
;                 if (fr2 == 0) d.xs[((size_t)((pn & 15) * 4 + wc2)) * (NBATCH * DM) + (size_t)b * DM + z * 256 + ai * 128 + wr2 * 64 + m * 16 + fq2 * 4 + j] = a;
;               }
;             }
; #pragma unroll
;             for (int i = 0; i < 2; ++i) {
;               const int row_l = i * 8 + rl;
;               f32x4 v = *(const f32x4*)&stg[row_l * 36 + c4];
;               u32x2 w = {pack2(v[0], v[1]), pack2(v[2], v[3])};
;               *(u32x2*)(outp + (size_t)(ai * 128 + wr2 * 64 + m * 16 + row_l) * 4096) = w;
;             }
.LBB0_244:
	v_mul_u32_u24_e32 v96, 0x90, v114
	v_add_u32_e32 v96, v117, v96
	s_waitcnt lgkmcnt(0)
	v_or_b32_e32 v97, 16, v132
	ds_read_b128 v[98:101], v96
	s_waitcnt lgkmcnt(0)
	v_cvt_pk_bf16_f32 v98, v98, v99
	v_cvt_pk_bf16_f32 v99, v100, v101
	v_or_b32_e32 v100, v97, v114
	v_ashrrev_i32_e32 v101, 31, v100
	v_lshlrev_b64 v[100:101], 13, v[100:101]
	v_lshl_add_u64 v[100:101], v[112:113], 0, v[100:101]
	global_store_dwordx2 v[100:101], v[98:99], off
	ds_read_b128 v[98:101], v96 offset:1152
	s_waitcnt lgkmcnt(0)
	v_cvt_pk_bf16_f32 v98, v98, v99
	v_cvt_pk_bf16_f32 v99, v100, v101
	v_or_b32_e32 v100, v115, v97
	v_ashrrev_i32_e32 v101, 31, v100
	v_lshlrev_b64 v[100:101], 13, v[100:101]
	v_mul_f32_e32 v84, v84, v152
	v_mul_f32_e32 v80, v80, v151
	v_lshl_add_u64 v[100:101], v[112:113], 0, v[100:101]
	v_fmac_f32_e32 v84, v92, v136
	v_fmac_f32_e32 v80, v88, v137
	s_and_b64 vcc, exec, s[16:17]
	global_store_dwordx2 v[100:101], v[98:99], off
	ds_write_b32 v120, v84
	ds_write_b32 v116, v80 offset:64
	s_cbranch_vccnz .LBB0_248
	v_add_f32_e32 v80, v84, v80
	v_cndmask_b32_e64 v80, -v80, v80, s[14:15]
	s_nop 1
	v_add_f32_dpp v80, v80, v80 quad_perm:[1,0,3,2] row_mask:0xf bank_mask:0xf
	s_nop 1
	v_add_f32_dpp v80, v80, v80 quad_perm:[2,3,0,1] row_mask:0xf bank_mask:0xf
	s_nop 1
	v_add_f32_dpp v80, v80, v80 row_half_mirror row_mask:0xf bank_mask:0xf
	s_nop 1
	v_add_f32_dpp v80, v80, v80 row_mirror row_mask:0xf bank_mask:0xf
	s_and_saveexec_b64 s[4:5], s[12:13]
	s_cbranch_execz .LBB0_247
	s_waitcnt lgkmcnt(0)
	global_store_dword v[134:135], v80, off offset:128

; template <int EPI>
; __device__ __forceinline__ void gemm_phase(const GemmDesc d, u16* shm, unsigned sx, unsigned srank, unsigned snloc) {
;     ...
;             for (int j = 0; j < 4; ++j) {
;               const float v0 = acc[ai][0][m][0][j] * rs0[0] + acc[ai][1][m][0][j] * rs1[0];
;               const float v1 = acc[ai][0][m][1][j] * rs0[1] + acc[ai][1][m][1][j] * rs1[1];
;               stg[(fq2 * 4 + j) * 36 + fr2] = v0; stg[(fq2 * 4 + j) * 36 + 16 + fr2] = v1;
;               if (pm == 0) {
;                 float a = (fr2 & 1) ? -(v0 + v1) : (v0 + v1);
;                 a += __shfl_xor(a, 1); a += __shfl_xor(a, 2); a += __shfl_xor(a, 4); a += __shfl_xor(a, 8);
;                 if (fr2 == 0) d.xs[((size_t)((pn & 15) * 4 + wc2)) * (NBATCH * DM) + (size_t)b * DM + z * 256 + ai * 128 + wr2 * 64 + m * 16 + fq2 * 4 + j] = a;
;               }
.LBB0_248:
	v_mul_f32_e32 v80, v85, v152
	v_mul_f32_e32 v81, v81, v151
	v_fmac_f32_e32 v80, v93, v136
	v_fmac_f32_e32 v81, v89, v137
	s_and_b64 vcc, exec, s[16:17]
	ds_write_b32 v120, v80 offset:144
	ds_write_b32 v116, v81 offset:208
	s_cbranch_vccnz .LBB0_252
	s_waitcnt lgkmcnt(2)
	v_add_f32_e32 v80, v80, v81
	v_cndmask_b32_e64 v80, -v80, v80, s[14:15]
	s_nop 1
	v_add_f32_dpp v80, v80, v80 quad_perm:[1,0,3,2] row_mask:0xf bank_mask:0xf
	s_nop 1
	v_add_f32_dpp v80, v80, v80 quad_perm:[2,3,0,1] row_mask:0xf bank_mask:0xf
	s_nop 1
	v_add_f32_dpp v80, v80, v80 row_half_mirror row_mask:0xf bank_mask:0xf
	s_nop 1
	v_add_f32_dpp v80, v80, v80 row_mirror row_mask:0xf bank_mask:0xf
	s_and_saveexec_b64 s[4:5], s[12:13]
	s_cbranch_execz .LBB0_251
	s_waitcnt lgkmcnt(0)
	global_store_dword v[134:135], v80, off offset:132

; template <int EPI>
; __device__ __forceinline__ void gemm_phase(const GemmDesc d, u16* shm, unsigned sx, unsigned srank, unsigned snloc) {
;     ...
;             for (int j = 0; j < 4; ++j) {
;               const float v0 = acc[ai][0][m][0][j] * rs0[0] + acc[ai][1][m][0][j] * rs1[0];
;               const float v1 = acc[ai][0][m][1][j] * rs0[1] + acc[ai][1][m][1][j] * rs1[1];
;               stg[(fq2 * 4 + j) * 36 + fr2] = v0; stg[(fq2 * 4 + j) * 36 + 16 + fr2] = v1;
;               if (pm == 0) {
;                 float a = (fr2 & 1) ? -(v0 + v1) : (v0 + v1);
;                 a += __shfl_xor(a, 1); a += __shfl_xor(a, 2); a += __shfl_xor(a, 4); a += __shfl_xor(a, 8);
;                 if (fr2 == 0) d.xs[((size_t)((pn & 15) * 4 + wc2)) * (NBATCH * DM) + (size_t)b * DM + z * 256 + ai * 128 + wr2 * 64 + m * 16 + fq2 * 4 + j] = a;
;               }
.LBB0_252:
	v_mul_f32_e32 v80, v86, v152
	s_waitcnt lgkmcnt(0)
	v_mul_f32_e32 v81, v82, v151
	v_fmac_f32_e32 v80, v94, v136
	v_fmac_f32_e32 v81, v90, v137
	s_and_b64 vcc, exec, s[16:17]
	ds_write_b32 v120, v80 offset:288
	ds_write_b32 v116, v81 offset:352
	s_cbranch_vccnz .LBB0_256
	v_add_f32_e32 v80, v80, v81
	v_cndmask_b32_e64 v80, -v80, v80, s[14:15]
	s_nop 1
	v_add_f32_dpp v80, v80, v80 quad_perm:[1,0,3,2] row_mask:0xf bank_mask:0xf
	s_nop 1
	v_add_f32_dpp v80, v80, v80 quad_perm:[2,3,0,1] row_mask:0xf bank_mask:0xf
	s_nop 1
	v_add_f32_dpp v80, v80, v80 row_half_mirror row_mask:0xf bank_mask:0xf
	s_nop 1
	v_add_f32_dpp v80, v80, v80 row_mirror row_mask:0xf bank_mask:0xf
	s_and_saveexec_b64 s[4:5], s[12:13]
	s_cbranch_execz .LBB0_255
	s_waitcnt lgkmcnt(0)
	global_store_dword v[134:135], v80, off offset:136

; template <int EPI>
; __device__ __forceinline__ void gemm_phase(const GemmDesc d, u16* shm, unsigned sx, unsigned srank, unsigned snloc) {
;     ...
;             for (int j = 0; j < 4; ++j) {
;               const float v0 = acc[ai][0][m][0][j] * rs0[0] + acc[ai][1][m][0][j] * rs1[0];
;               const float v1 = acc[ai][0][m][1][j] * rs0[1] + acc[ai][1][m][1][j] * rs1[1];
;               stg[(fq2 * 4 + j) * 36 + fr2] = v0; stg[(fq2 * 4 + j) * 36 + 16 + fr2] = v1;
;               if (pm == 0) {
;                 float a = (fr2 & 1) ? -(v0 + v1) : (v0 + v1);
;                 a += __shfl_xor(a, 1); a += __shfl_xor(a, 2); a += __shfl_xor(a, 4); a += __shfl_xor(a, 8);
;                 if (fr2 == 0) d.xs[((size_t)((pn & 15) * 4 + wc2)) * (NBATCH * DM) + (size_t)b * DM + z * 256 + ai * 128 + wr2 * 64 + m * 16 + fq2 * 4 + j] = a;
;               }
.LBB0_256:
	v_mul_f32_e32 v80, v87, v152
	s_waitcnt lgkmcnt(0)
	v_mul_f32_e32 v81, v83, v151
	v_fmac_f32_e32 v80, v95, v136
	v_fmac_f32_e32 v81, v91, v137
	s_and_b64 vcc, exec, s[16:17]
	ds_write_b32 v120, v80 offset:432
	ds_write_b32 v116, v81 offset:496
	s_cbranch_vccnz .LBB0_260
	v_add_f32_e32 v80, v80, v81
	v_cndmask_b32_e64 v80, -v80, v80, s[14:15]
	s_nop 1
	v_add_f32_dpp v80, v80, v80 quad_perm:[1,0,3,2] row_mask:0xf bank_mask:0xf
	s_nop 1
	v_add_f32_dpp v80, v80, v80 quad_perm:[2,3,0,1] row_mask:0xf bank_mask:0xf
	s_nop 1
	v_add_f32_dpp v80, v80, v80 row_half_mirror row_mask:0xf bank_mask:0xf
	s_nop 1
	v_add_f32_dpp v80, v80, v80 row_mirror row_mask:0xf bank_mask:0xf
	s_and_saveexec_b64 s[4:5], s[12:13]
	s_cbranch_execz .LBB0_259
	s_waitcnt lgkmcnt(0)
	global_store_dword v[134:135], v80, off offset:140

; __device__ __forceinline__ unsigned pack2(float lo, float hi) { unsigned r; asm volatile("v_cvt_pk_bf16_f32 %0, %1, %2" : "=v"(r) : "v"(lo), "v"(hi)); return r; }
; template <int EPI>
; __device__ __forceinline__ void gemm_phase(const GemmDesc d, u16* shm, unsigned sx, unsigned srank, unsigned snloc) {
;     ...
;               const float v0 = acc[ai][0][m][0][j] * rs0[0] + acc[ai][1][m][0][j] * rs1[0];
;               const float v1 = acc[ai][0][m][1][j] * rs0[1] + acc[ai][1][m][1][j] * rs1[1];
;               stg[(fq2 * 4 + j) * 36 + fr2] = v0; stg[(fq2 * 4 + j) * 36 + 16 + fr2] = v1;
;               if (pm == 0) {
;                 float a = (fr2 & 1) ? -(v0 + v1) : (v0 + v1);
;                 a += __shfl_xor(a, 1); a += __shfl_xor(a, 2); a += __shfl_xor(a, 4); a += __shfl_xor(a, 8);
;                 if (fr2 == 0) d.xs[((size_t)((pn & 15) * 4 + wc2)) * (NBATCH * DM) + (size_t)b * DM + z * 256 + ai * 128 + wr2 * 64 + m * 16 + fq2 * 4 + j] = a;
;               }
;             }
; #pragma unroll
;             for (int i = 0; i < 2; ++i) {
;               const int row_l = i * 8 + rl;
;               f32x4 v = *(const f32x4*)&stg[row_l * 36 + c4];
;               u32x2 w = {pack2(v[0], v[1]), pack2(v[2], v[3])};
;               *(u32x2*)(outp + (size_t)(ai * 128 + wr2 * 64 + m * 16 + row_l) * 4096) = w;
;             }
.LBB0_260:
	v_or_b32_e32 v84, 32, v132
	s_waitcnt lgkmcnt(0)
	ds_read_b128 v[80:83], v96
	s_waitcnt lgkmcnt(0)
	v_cvt_pk_bf16_f32 v80, v80, v81
	v_cvt_pk_bf16_f32 v81, v82, v83
	v_or_b32_e32 v82, v84, v114
	v_ashrrev_i32_e32 v83, 31, v82
	v_lshlrev_b64 v[82:83], 13, v[82:83]
	v_lshl_add_u64 v[82:83], v[112:113], 0, v[82:83]
	global_store_dwordx2 v[82:83], v[80:81], off
	ds_read_b128 v[80:83], v96 offset:1152
	s_waitcnt lgkmcnt(0)
	v_cvt_pk_bf16_f32 v80, v80, v81
	v_cvt_pk_bf16_f32 v81, v82, v83
	v_or_b32_e32 v82, v115, v84
	v_ashrrev_i32_e32 v83, 31, v82
	v_lshlrev_b64 v[82:83], 13, v[82:83]
	v_mul_f32_e32 v68, v68, v152
	v_mul_f32_e32 v64, v64, v151
	v_lshl_add_u64 v[82:83], v[112:113], 0, v[82:83]
	v_fmac_f32_e32 v68, v76, v136
	v_fmac_f32_e32 v64, v72, v137
	s_and_b64 vcc, exec, s[16:17]
	global_store_dwordx2 v[82:83], v[80:81], off
	ds_write_b32 v120, v68
	ds_write_b32 v116, v64 offset:64
	s_cbranch_vccnz .LBB0_264
	v_add_f32_e32 v64, v68, v64
	v_cndmask_b32_e64 v64, -v64, v64, s[14:15]
	s_nop 1
	v_add_f32_dpp v64, v64, v64 quad_perm:[1,0,3,2] row_mask:0xf bank_mask:0xf
	s_nop 1
	v_add_f32_dpp v64, v64, v64 quad_perm:[2,3,0,1] row_mask:0xf bank_mask:0xf
	s_nop 1
	v_add_f32_dpp v64, v64, v64 row_half_mirror row_mask:0xf bank_mask:0xf
	s_nop 1
	v_add_f32_dpp v64, v64, v64 row_mirror row_mask:0xf bank_mask:0xf
	s_and_saveexec_b64 s[4:5], s[12:13]
	s_cbranch_execz .LBB0_263
	s_waitcnt lgkmcnt(0)
	global_store_dword v[134:135], v64, off offset:192

; template <int EPI>
; __device__ __forceinline__ void gemm_phase(const GemmDesc d, u16* shm, unsigned sx, unsigned srank, unsigned snloc) {
;     ...
;             for (int j = 0; j < 4; ++j) {
;               const float v0 = acc[ai][0][m][0][j] * rs0[0] + acc[ai][1][m][0][j] * rs1[0];
;               const float v1 = acc[ai][0][m][1][j] * rs0[1] + acc[ai][1][m][1][j] * rs1[1];
;               stg[(fq2 * 4 + j) * 36 + fr2] = v0; stg[(fq2 * 4 + j) * 36 + 16 + fr2] = v1;
;               if (pm == 0) {
;                 float a = (fr2 & 1) ? -(v0 + v1) : (v0 + v1);
;                 a += __shfl_xor(a, 1); a += __shfl_xor(a, 2); a += __shfl_xor(a, 4); a += __shfl_xor(a, 8);
;                 if (fr2 == 0) d.xs[((size_t)((pn & 15) * 4 + wc2)) * (NBATCH * DM) + (size_t)b * DM + z * 256 + ai * 128 + wr2 * 64 + m * 16 + fq2 * 4 + j] = a;
;               }
.LBB0_264:
	v_mul_f32_e32 v64, v69, v152
	v_mul_f32_e32 v65, v65, v151
	v_fmac_f32_e32 v64, v77, v136
	v_fmac_f32_e32 v65, v73, v137
	s_and_b64 vcc, exec, s[16:17]
	ds_write_b32 v120, v64 offset:144
	ds_write_b32 v116, v65 offset:208
	s_cbranch_vccnz .LBB0_268
	s_waitcnt lgkmcnt(2)
	v_add_f32_e32 v64, v64, v65
	v_cndmask_b32_e64 v64, -v64, v64, s[14:15]
	s_nop 1
	v_add_f32_dpp v64, v64, v64 quad_perm:[1,0,3,2] row_mask:0xf bank_mask:0xf
	s_nop 1
	v_add_f32_dpp v64, v64, v64 quad_perm:[2,3,0,1] row_mask:0xf bank_mask:0xf
	s_nop 1
	v_add_f32_dpp v64, v64, v64 row_half_mirror row_mask:0xf bank_mask:0xf
	s_nop 1
	v_add_f32_dpp v64, v64, v64 row_mirror row_mask:0xf bank_mask:0xf
	s_and_saveexec_b64 s[4:5], s[12:13]
	s_cbranch_execz .LBB0_267
	s_waitcnt lgkmcnt(0)
	global_store_dword v[134:135], v64, off offset:196

; template <int EPI>
; __device__ __forceinline__ void gemm_phase(const GemmDesc d, u16* shm, unsigned sx, unsigned srank, unsigned snloc) {
;     ...
;             for (int j = 0; j < 4; ++j) {
;               const float v0 = acc[ai][0][m][0][j] * rs0[0] + acc[ai][1][m][0][j] * rs1[0];
;               const float v1 = acc[ai][0][m][1][j] * rs0[1] + acc[ai][1][m][1][j] * rs1[1];
;               stg[(fq2 * 4 + j) * 36 + fr2] = v0; stg[(fq2 * 4 + j) * 36 + 16 + fr2] = v1;
;               if (pm == 0) {
;                 float a = (fr2 & 1) ? -(v0 + v1) : (v0 + v1);
;                 a += __shfl_xor(a, 1); a += __shfl_xor(a, 2); a += __shfl_xor(a, 4); a += __shfl_xor(a, 8);
;                 if (fr2 == 0) d.xs[((size_t)((pn & 15) * 4 + wc2)) * (NBATCH * DM) + (size_t)b * DM + z * 256 + ai * 128 + wr2 * 64 + m * 16 + fq2 * 4 + j] = a;
;               }
.LBB0_268:
	v_mul_f32_e32 v64, v70, v152
	s_waitcnt lgkmcnt(0)
	v_mul_f32_e32 v65, v66, v151
	v_fmac_f32_e32 v64, v78, v136
	v_fmac_f32_e32 v65, v74, v137
	s_and_b64 vcc, exec, s[16:17]
	ds_write_b32 v120, v64 offset:288
	ds_write_b32 v116, v65 offset:352
	s_cbranch_vccnz .LBB0_272
	v_add_f32_e32 v64, v64, v65
	v_cndmask_b32_e64 v64, -v64, v64, s[14:15]
	s_nop 1
	v_add_f32_dpp v64, v64, v64 quad_perm:[1,0,3,2] row_mask:0xf bank_mask:0xf
	s_nop 1
	v_add_f32_dpp v64, v64, v64 quad_perm:[2,3,0,1] row_mask:0xf bank_mask:0xf
	s_nop 1
	v_add_f32_dpp v64, v64, v64 row_half_mirror row_mask:0xf bank_mask:0xf
	s_nop 1
	v_add_f32_dpp v64, v64, v64 row_mirror row_mask:0xf bank_mask:0xf
	s_and_saveexec_b64 s[4:5], s[12:13]
	s_cbranch_execz .LBB0_271
	s_waitcnt lgkmcnt(0)
	global_store_dword v[134:135], v64, off offset:200

; template <int EPI>
; __device__ __forceinline__ void gemm_phase(const GemmDesc d, u16* shm, unsigned sx, unsigned srank, unsigned snloc) {
;     ...
;             for (int j = 0; j < 4; ++j) {
;               const float v0 = acc[ai][0][m][0][j] * rs0[0] + acc[ai][1][m][0][j] * rs1[0];
;               const float v1 = acc[ai][0][m][1][j] * rs0[1] + acc[ai][1][m][1][j] * rs1[1];
;               stg[(fq2 * 4 + j) * 36 + fr2] = v0; stg[(fq2 * 4 + j) * 36 + 16 + fr2] = v1;
;               if (pm == 0) {
;                 float a = (fr2 & 1) ? -(v0 + v1) : (v0 + v1);
;                 a += __shfl_xor(a, 1); a += __shfl_xor(a, 2); a += __shfl_xor(a, 4); a += __shfl_xor(a, 8);
;                 if (fr2 == 0) d.xs[((size_t)((pn & 15) * 4 + wc2)) * (NBATCH * DM) + (size_t)b * DM + z * 256 + ai * 128 + wr2 * 64 + m * 16 + fq2 * 4 + j] = a;
;               }
.LBB0_272:
	v_mul_f32_e32 v64, v71, v152
	s_waitcnt lgkmcnt(0)
	v_mul_f32_e32 v65, v67, v151
	v_fmac_f32_e32 v64, v79, v136
	v_fmac_f32_e32 v65, v75, v137
	s_and_b64 vcc, exec, s[16:17]
	ds_write_b32 v120, v64 offset:432
	ds_write_b32 v116, v65 offset:496
	s_cbranch_vccnz .LBB0_276
	v_add_f32_e32 v64, v64, v65
	v_cndmask_b32_e64 v64, -v64, v64, s[14:15]
	s_nop 1
	v_add_f32_dpp v64, v64, v64 quad_perm:[1,0,3,2] row_mask:0xf bank_mask:0xf
	s_nop 1
	v_add_f32_dpp v64, v64, v64 quad_perm:[2,3,0,1] row_mask:0xf bank_mask:0xf
	s_nop 1
	v_add_f32_dpp v64, v64, v64 row_half_mirror row_mask:0xf bank_mask:0xf
	s_nop 1
	v_add_f32_dpp v64, v64, v64 row_mirror row_mask:0xf bank_mask:0xf
	s_and_saveexec_b64 s[4:5], s[12:13]
	s_cbranch_execz .LBB0_275
	s_waitcnt lgkmcnt(0)
	global_store_dword v[134:135], v64, off offset:204

; __device__ __forceinline__ unsigned pack2(float lo, float hi) { unsigned r; asm volatile("v_cvt_pk_bf16_f32 %0, %1, %2" : "=v"(r) : "v"(lo), "v"(hi)); return r; }
; template <int EPI>
; __device__ __forceinline__ void gemm_phase(const GemmDesc d, u16* shm, unsigned sx, unsigned srank, unsigned snloc) {
;     ...
;               const float v0 = acc[ai][0][m][0][j] * rs0[0] + acc[ai][1][m][0][j] * rs1[0];
;               const float v1 = acc[ai][0][m][1][j] * rs0[1] + acc[ai][1][m][1][j] * rs1[1];
;               stg[(fq2 * 4 + j) * 36 + fr2] = v0; stg[(fq2 * 4 + j) * 36 + 16 + fr2] = v1;
;               if (pm == 0) {
;                 float a = (fr2 & 1) ? -(v0 + v1) : (v0 + v1);
;                 a += __shfl_xor(a, 1); a += __shfl_xor(a, 2); a += __shfl_xor(a, 4); a += __shfl_xor(a, 8);
;                 if (fr2 == 0) d.xs[((size_t)((pn & 15) * 4 + wc2)) * (NBATCH * DM) + (size_t)b * DM + z * 256 + ai * 128 + wr2 * 64 + m * 16 + fq2 * 4 + j] = a;
;               }
;             }
; #pragma unroll
;             for (int i = 0; i < 2; ++i) {
;               const int row_l = i * 8 + rl;
;               f32x4 v = *(const f32x4*)&stg[row_l * 36 + c4];
;               u32x2 w = {pack2(v[0], v[1]), pack2(v[2], v[3])};
;               *(u32x2*)(outp + (size_t)(ai * 128 + wr2 * 64 + m * 16 + row_l) * 4096) = w;
;             }
.LBB0_276:
	v_or_b32_e32 v68, 48, v132
	s_waitcnt lgkmcnt(0)
	ds_read_b128 v[64:67], v96
	s_waitcnt lgkmcnt(0)
	v_cvt_pk_bf16_f32 v64, v64, v65
	v_cvt_pk_bf16_f32 v65, v66, v67
	v_or_b32_e32 v66, v68, v114
	v_ashrrev_i32_e32 v67, 31, v66
	v_lshlrev_b64 v[66:67], 13, v[66:67]
	v_lshl_add_u64 v[66:67], v[112:113], 0, v[66:67]
	global_store_dwordx2 v[66:67], v[64:65], off
	ds_read_b128 v[64:67], v96 offset:1152
	s_waitcnt lgkmcnt(0)
	v_cvt_pk_bf16_f32 v64, v64, v65
	v_cvt_pk_bf16_f32 v65, v66, v67
	v_or_b32_e32 v66, v115, v68
	v_ashrrev_i32_e32 v67, 31, v66
	v_lshlrev_b64 v[66:67], 13, v[66:67]
	v_mul_f32_e32 v52, v52, v152
	v_mul_f32_e32 v48, v48, v151
	v_lshl_add_u64 v[66:67], v[112:113], 0, v[66:67]
	v_fmac_f32_e32 v52, v60, v136
	v_fmac_f32_e32 v48, v56, v137
	s_and_b64 vcc, exec, s[16:17]
	global_store_dwordx2 v[66:67], v[64:65], off
	ds_write_b32 v120, v52
	ds_write_b32 v116, v48 offset:64
	s_cbranch_vccnz .LBB0_280
	v_add_f32_e32 v48, v52, v48
	v_cndmask_b32_e64 v48, -v48, v48, s[14:15]
	s_nop 1
	v_add_f32_dpp v48, v48, v48 quad_perm:[1,0,3,2] row_mask:0xf bank_mask:0xf
	s_nop 1
	v_add_f32_dpp v48, v48, v48 quad_perm:[2,3,0,1] row_mask:0xf bank_mask:0xf
	s_nop 1
	v_add_f32_dpp v48, v48, v48 row_half_mirror row_mask:0xf bank_mask:0xf
	s_nop 1
	v_add_f32_dpp v48, v48, v48 row_mirror row_mask:0xf bank_mask:0xf
	s_and_saveexec_b64 s[4:5], s[12:13]
	s_cbranch_execz .LBB0_279
	s_waitcnt lgkmcnt(0)
	global_store_dword v[134:135], v48, off offset:512

; template <int EPI>
; __device__ __forceinline__ void gemm_phase(const GemmDesc d, u16* shm, unsigned sx, unsigned srank, unsigned snloc) {
;     ...
;             for (int j = 0; j < 4; ++j) {
;               const float v0 = acc[ai][0][m][0][j] * rs0[0] + acc[ai][1][m][0][j] * rs1[0];
;               const float v1 = acc[ai][0][m][1][j] * rs0[1] + acc[ai][1][m][1][j] * rs1[1];
;               stg[(fq2 * 4 + j) * 36 + fr2] = v0; stg[(fq2 * 4 + j) * 36 + 16 + fr2] = v1;
;               if (pm == 0) {
;                 float a = (fr2 & 1) ? -(v0 + v1) : (v0 + v1);
;                 a += __shfl_xor(a, 1); a += __shfl_xor(a, 2); a += __shfl_xor(a, 4); a += __shfl_xor(a, 8);
;                 if (fr2 == 0) d.xs[((size_t)((pn & 15) * 4 + wc2)) * (NBATCH * DM) + (size_t)b * DM + z * 256 + ai * 128 + wr2 * 64 + m * 16 + fq2 * 4 + j] = a;
;               }
.LBB0_280:
	v_mul_f32_e32 v48, v53, v152
	v_mul_f32_e32 v49, v49, v151
	v_fmac_f32_e32 v48, v61, v136
	v_fmac_f32_e32 v49, v57, v137
	s_and_b64 vcc, exec, s[16:17]
	ds_write_b32 v120, v48 offset:144
	ds_write_b32 v116, v49 offset:208
	s_cbranch_vccnz .LBB0_284
	s_waitcnt lgkmcnt(2)
	v_add_f32_e32 v48, v48, v49
	v_cndmask_b32_e64 v48, -v48, v48, s[14:15]
	s_nop 1
	v_add_f32_dpp v48, v48, v48 quad_perm:[1,0,3,2] row_mask:0xf bank_mask:0xf
	s_nop 1
	v_add_f32_dpp v48, v48, v48 quad_perm:[2,3,0,1] row_mask:0xf bank_mask:0xf
	s_nop 1
	v_add_f32_dpp v48, v48, v48 row_half_mirror row_mask:0xf bank_mask:0xf
	s_nop 1
	v_add_f32_dpp v48, v48, v48 row_mirror row_mask:0xf bank_mask:0xf
	s_and_saveexec_b64 s[4:5], s[12:13]
	s_cbranch_execz .LBB0_283
	s_waitcnt lgkmcnt(0)
	global_store_dword v[134:135], v48, off offset:516

; template <int EPI>
; __device__ __forceinline__ void gemm_phase(const GemmDesc d, u16* shm, unsigned sx, unsigned srank, unsigned snloc) {
;     ...
;             for (int j = 0; j < 4; ++j) {
;               const float v0 = acc[ai][0][m][0][j] * rs0[0] + acc[ai][1][m][0][j] * rs1[0];
;               const float v1 = acc[ai][0][m][1][j] * rs0[1] + acc[ai][1][m][1][j] * rs1[1];
;               stg[(fq2 * 4 + j) * 36 + fr2] = v0; stg[(fq2 * 4 + j) * 36 + 16 + fr2] = v1;
;               if (pm == 0) {
;                 float a = (fr2 & 1) ? -(v0 + v1) : (v0 + v1);
;                 a += __shfl_xor(a, 1); a += __shfl_xor(a, 2); a += __shfl_xor(a, 4); a += __shfl_xor(a, 8);
;                 if (fr2 == 0) d.xs[((size_t)((pn & 15) * 4 + wc2)) * (NBATCH * DM) + (size_t)b * DM + z * 256 + ai * 128 + wr2 * 64 + m * 16 + fq2 * 4 + j] = a;
;               }
.LBB0_284:
	v_mul_f32_e32 v48, v54, v152
	s_waitcnt lgkmcnt(0)
	v_mul_f32_e32 v49, v50, v151
	v_fmac_f32_e32 v48, v62, v136
	v_fmac_f32_e32 v49, v58, v137
	s_and_b64 vcc, exec, s[16:17]
	ds_write_b32 v120, v48 offset:288
	ds_write_b32 v116, v49 offset:352
	s_cbranch_vccnz .LBB0_288
	v_add_f32_e32 v48, v48, v49
	v_cndmask_b32_e64 v48, -v48, v48, s[14:15]
	s_nop 1
	v_add_f32_dpp v48, v48, v48 quad_perm:[1,0,3,2] row_mask:0xf bank_mask:0xf
	s_nop 1
	v_add_f32_dpp v48, v48, v48 quad_perm:[2,3,0,1] row_mask:0xf bank_mask:0xf
	s_nop 1
	v_add_f32_dpp v48, v48, v48 row_half_mirror row_mask:0xf bank_mask:0xf
	s_nop 1
	v_add_f32_dpp v48, v48, v48 row_mirror row_mask:0xf bank_mask:0xf
	s_and_saveexec_b64 s[4:5], s[12:13]
	s_cbranch_execz .LBB0_287
	s_waitcnt lgkmcnt(0)
	global_store_dword v[134:135], v48, off offset:520

; template <int EPI>
; __device__ __forceinline__ void gemm_phase(const GemmDesc d, u16* shm, unsigned sx, unsigned srank, unsigned snloc) {
;     ...
;             for (int j = 0; j < 4; ++j) {
;               const float v0 = acc[ai][0][m][0][j] * rs0[0] + acc[ai][1][m][0][j] * rs1[0];
;               const float v1 = acc[ai][0][m][1][j] * rs0[1] + acc[ai][1][m][1][j] * rs1[1];
;               stg[(fq2 * 4 + j) * 36 + fr2] = v0; stg[(fq2 * 4 + j) * 36 + 16 + fr2] = v1;
;               if (pm == 0) {
;                 float a = (fr2 & 1) ? -(v0 + v1) : (v0 + v1);
;                 a += __shfl_xor(a, 1); a += __shfl_xor(a, 2); a += __shfl_xor(a, 4); a += __shfl_xor(a, 8);
;                 if (fr2 == 0) d.xs[((size_t)((pn & 15) * 4 + wc2)) * (NBATCH * DM) + (size_t)b * DM + z * 256 + ai * 128 + wr2 * 64 + m * 16 + fq2 * 4 + j] = a;
;               }
.LBB0_288:
	v_mul_f32_e32 v48, v55, v152
	s_waitcnt lgkmcnt(0)
	v_mul_f32_e32 v49, v51, v151
	v_fmac_f32_e32 v48, v63, v136
	v_fmac_f32_e32 v49, v59, v137
	s_and_b64 vcc, exec, s[16:17]
	ds_write_b32 v120, v48 offset:432
	ds_write_b32 v116, v49 offset:496
	s_cbranch_vccnz .LBB0_292
	v_add_f32_e32 v48, v48, v49
	v_cndmask_b32_e64 v48, -v48, v48, s[14:15]
	s_nop 1
	v_add_f32_dpp v48, v48, v48 quad_perm:[1,0,3,2] row_mask:0xf bank_mask:0xf
	s_nop 1
	v_add_f32_dpp v48, v48, v48 quad_perm:[2,3,0,1] row_mask:0xf bank_mask:0xf
	s_nop 1
	v_add_f32_dpp v48, v48, v48 row_half_mirror row_mask:0xf bank_mask:0xf
	s_nop 1
	v_add_f32_dpp v48, v48, v48 row_mirror row_mask:0xf bank_mask:0xf
	s_and_saveexec_b64 s[4:5], s[12:13]
	s_cbranch_execz .LBB0_291
	s_waitcnt lgkmcnt(0)
	global_store_dword v[134:135], v48, off offset:524

; __device__ __forceinline__ unsigned pack2(float lo, float hi) { unsigned r; asm volatile("v_cvt_pk_bf16_f32 %0, %1, %2" : "=v"(r) : "v"(lo), "v"(hi)); return r; }
; template <int EPI>
; __device__ __forceinline__ void gemm_phase(const GemmDesc d, u16* shm, unsigned sx, unsigned srank, unsigned snloc) {
;     ...
;               const float v0 = acc[ai][0][m][0][j] * rs0[0] + acc[ai][1][m][0][j] * rs1[0];
;               const float v1 = acc[ai][0][m][1][j] * rs0[1] + acc[ai][1][m][1][j] * rs1[1];
;               stg[(fq2 * 4 + j) * 36 + fr2] = v0; stg[(fq2 * 4 + j) * 36 + 16 + fr2] = v1;
;               if (pm == 0) {
;                 float a = (fr2 & 1) ? -(v0 + v1) : (v0 + v1);
;                 a += __shfl_xor(a, 1); a += __shfl_xor(a, 2); a += __shfl_xor(a, 4); a += __shfl_xor(a, 8);
;                 if (fr2 == 0) d.xs[((size_t)((pn & 15) * 4 + wc2)) * (NBATCH * DM) + (size_t)b * DM + z * 256 + ai * 128 + wr2 * 64 + m * 16 + fq2 * 4 + j] = a;
;               }
;             }
; #pragma unroll
;             for (int i = 0; i < 2; ++i) {
;               const int row_l = i * 8 + rl;
;               f32x4 v = *(const f32x4*)&stg[row_l * 36 + c4];
;               u32x2 w = {pack2(v[0], v[1]), pack2(v[2], v[3])};
;               *(u32x2*)(outp + (size_t)(ai * 128 + wr2 * 64 + m * 16 + row_l) * 4096) = w;
;             }
.LBB0_292:
	v_add_u32_e32 v52, 0x80, v132
	s_waitcnt lgkmcnt(0)
	ds_read_b128 v[48:51], v96
	s_waitcnt lgkmcnt(0)
	v_cvt_pk_bf16_f32 v48, v48, v49
	v_cvt_pk_bf16_f32 v49, v50, v51
	v_or_b32_e32 v50, v52, v114
	v_ashrrev_i32_e32 v51, 31, v50
	v_lshlrev_b64 v[50:51], 13, v[50:51]
	v_lshl_add_u64 v[50:51], v[112:113], 0, v[50:51]
	global_store_dwordx2 v[50:51], v[48:49], off
	ds_read_b128 v[48:51], v96 offset:1152
	s_waitcnt lgkmcnt(0)
	v_cvt_pk_bf16_f32 v48, v48, v49
	v_cvt_pk_bf16_f32 v49, v50, v51
	v_or_b32_e32 v50, v115, v52
	v_ashrrev_i32_e32 v51, 31, v50
	v_lshlrev_b64 v[50:51], 13, v[50:51]
	v_mul_f32_e32 v36, v36, v152
	v_mul_f32_e32 v32, v32, v151
	v_lshl_add_u64 v[50:51], v[112:113], 0, v[50:51]
	v_fmac_f32_e32 v36, v44, v136
	v_fmac_f32_e32 v32, v40, v137
	s_and_b64 vcc, exec, s[16:17]
	global_store_dwordx2 v[50:51], v[48:49], off
	ds_write_b32 v120, v36
	ds_write_b32 v116, v32 offset:64
	s_cbranch_vccnz .LBB0_296
	v_add_f32_e32 v32, v36, v32
	v_cndmask_b32_e64 v32, -v32, v32, s[14:15]
	s_nop 1
	v_add_f32_dpp v32, v32, v32 quad_perm:[1,0,3,2] row_mask:0xf bank_mask:0xf
	s_nop 1
	v_add_f32_dpp v32, v32, v32 quad_perm:[2,3,0,1] row_mask:0xf bank_mask:0xf
	s_nop 1
	v_add_f32_dpp v32, v32, v32 row_half_mirror row_mask:0xf bank_mask:0xf
	s_nop 1
	v_add_f32_dpp v32, v32, v32 row_mirror row_mask:0xf bank_mask:0xf
	s_and_saveexec_b64 s[4:5], s[12:13]
	s_cbranch_execz .LBB0_295
	s_waitcnt lgkmcnt(0)
	global_store_dword v[134:135], v32, off offset:576

; template <int EPI>
; __device__ __forceinline__ void gemm_phase(const GemmDesc d, u16* shm, unsigned sx, unsigned srank, unsigned snloc) {
;     ...
;             for (int j = 0; j < 4; ++j) {
;               const float v0 = acc[ai][0][m][0][j] * rs0[0] + acc[ai][1][m][0][j] * rs1[0];
;               const float v1 = acc[ai][0][m][1][j] * rs0[1] + acc[ai][1][m][1][j] * rs1[1];
;               stg[(fq2 * 4 + j) * 36 + fr2] = v0; stg[(fq2 * 4 + j) * 36 + 16 + fr2] = v1;
;               if (pm == 0) {
;                 float a = (fr2 & 1) ? -(v0 + v1) : (v0 + v1);
;                 a += __shfl_xor(a, 1); a += __shfl_xor(a, 2); a += __shfl_xor(a, 4); a += __shfl_xor(a, 8);
;                 if (fr2 == 0) d.xs[((size_t)((pn & 15) * 4 + wc2)) * (NBATCH * DM) + (size_t)b * DM + z * 256 + ai * 128 + wr2 * 64 + m * 16 + fq2 * 4 + j] = a;
;               }
.LBB0_296:
	v_mul_f32_e32 v32, v37, v152
	v_mul_f32_e32 v33, v33, v151
	v_fmac_f32_e32 v32, v45, v136
	v_fmac_f32_e32 v33, v41, v137
	s_and_b64 vcc, exec, s[16:17]
	ds_write_b32 v120, v32 offset:144
	ds_write_b32 v116, v33 offset:208
	s_cbranch_vccnz .LBB0_300
	s_waitcnt lgkmcnt(2)
	v_add_f32_e32 v32, v32, v33
	v_cndmask_b32_e64 v32, -v32, v32, s[14:15]
	s_nop 1
	v_add_f32_dpp v32, v32, v32 quad_perm:[1,0,3,2] row_mask:0xf bank_mask:0xf
	s_nop 1
	v_add_f32_dpp v32, v32, v32 quad_perm:[2,3,0,1] row_mask:0xf bank_mask:0xf
	s_nop 1
	v_add_f32_dpp v32, v32, v32 row_half_mirror row_mask:0xf bank_mask:0xf
	s_nop 1
	v_add_f32_dpp v32, v32, v32 row_mirror row_mask:0xf bank_mask:0xf
	s_and_saveexec_b64 s[4:5], s[12:13]
	s_cbranch_execz .LBB0_299
	s_waitcnt lgkmcnt(0)
	global_store_dword v[134:135], v32, off offset:580

; template <int EPI>
; __device__ __forceinline__ void gemm_phase(const GemmDesc d, u16* shm, unsigned sx, unsigned srank, unsigned snloc) {
;     ...
;             for (int j = 0; j < 4; ++j) {
;               const float v0 = acc[ai][0][m][0][j] * rs0[0] + acc[ai][1][m][0][j] * rs1[0];
;               const float v1 = acc[ai][0][m][1][j] * rs0[1] + acc[ai][1][m][1][j] * rs1[1];
;               stg[(fq2 * 4 + j) * 36 + fr2] = v0; stg[(fq2 * 4 + j) * 36 + 16 + fr2] = v1;
;               if (pm == 0) {
;                 float a = (fr2 & 1) ? -(v0 + v1) : (v0 + v1);
;                 a += __shfl_xor(a, 1); a += __shfl_xor(a, 2); a += __shfl_xor(a, 4); a += __shfl_xor(a, 8);
;                 if (fr2 == 0) d.xs[((size_t)((pn & 15) * 4 + wc2)) * (NBATCH * DM) + (size_t)b * DM + z * 256 + ai * 128 + wr2 * 64 + m * 16 + fq2 * 4 + j] = a;
;               }
.LBB0_300:
	v_mul_f32_e32 v32, v38, v152
	s_waitcnt lgkmcnt(0)
	v_mul_f32_e32 v33, v34, v151
	v_fmac_f32_e32 v32, v46, v136
	v_fmac_f32_e32 v33, v42, v137
	s_and_b64 vcc, exec, s[16:17]
	ds_write_b32 v120, v32 offset:288
	ds_write_b32 v116, v33 offset:352
	s_cbranch_vccnz .LBB0_304
	v_add_f32_e32 v32, v32, v33
	v_cndmask_b32_e64 v32, -v32, v32, s[14:15]
	s_nop 1
	v_add_f32_dpp v32, v32, v32 quad_perm:[1,0,3,2] row_mask:0xf bank_mask:0xf
	s_nop 1
	v_add_f32_dpp v32, v32, v32 quad_perm:[2,3,0,1] row_mask:0xf bank_mask:0xf
	s_nop 1
	v_add_f32_dpp v32, v32, v32 row_half_mirror row_mask:0xf bank_mask:0xf
	s_nop 1
	v_add_f32_dpp v32, v32, v32 row_mirror row_mask:0xf bank_mask:0xf
	s_and_saveexec_b64 s[4:5], s[12:13]
	s_cbranch_execz .LBB0_303
	s_waitcnt lgkmcnt(0)
	global_store_dword v[134:135], v32, off offset:584

; template <int EPI>
; __device__ __forceinline__ void gemm_phase(const GemmDesc d, u16* shm, unsigned sx, unsigned srank, unsigned snloc) {
;     ...
;             for (int j = 0; j < 4; ++j) {
;               const float v0 = acc[ai][0][m][0][j] * rs0[0] + acc[ai][1][m][0][j] * rs1[0];
;               const float v1 = acc[ai][0][m][1][j] * rs0[1] + acc[ai][1][m][1][j] * rs1[1];
;               stg[(fq2 * 4 + j) * 36 + fr2] = v0; stg[(fq2 * 4 + j) * 36 + 16 + fr2] = v1;
;               if (pm == 0) {
;                 float a = (fr2 & 1) ? -(v0 + v1) : (v0 + v1);
;                 a += __shfl_xor(a, 1); a += __shfl_xor(a, 2); a += __shfl_xor(a, 4); a += __shfl_xor(a, 8);
;                 if (fr2 == 0) d.xs[((size_t)((pn & 15) * 4 + wc2)) * (NBATCH * DM) + (size_t)b * DM + z * 256 + ai * 128 + wr2 * 64 + m * 16 + fq2 * 4 + j] = a;
;               }
.LBB0_304:
	v_mul_f32_e32 v32, v39, v152
	s_waitcnt lgkmcnt(0)
	v_mul_f32_e32 v33, v35, v151
	v_fmac_f32_e32 v32, v47, v136
	v_fmac_f32_e32 v33, v43, v137
	s_and_b64 vcc, exec, s[16:17]
	ds_write_b32 v120, v32 offset:432
	ds_write_b32 v116, v33 offset:496
	s_cbranch_vccnz .LBB0_308
	v_add_f32_e32 v32, v32, v33
	v_cndmask_b32_e64 v32, -v32, v32, s[14:15]
	s_nop 1
	v_add_f32_dpp v32, v32, v32 quad_perm:[1,0,3,2] row_mask:0xf bank_mask:0xf
	s_nop 1
	v_add_f32_dpp v32, v32, v32 quad_perm:[2,3,0,1] row_mask:0xf bank_mask:0xf
	s_nop 1
	v_add_f32_dpp v32, v32, v32 row_half_mirror row_mask:0xf bank_mask:0xf
	s_nop 1
	v_add_f32_dpp v32, v32, v32 row_mirror row_mask:0xf bank_mask:0xf
	s_and_saveexec_b64 s[4:5], s[12:13]
	s_cbranch_execz .LBB0_307
	s_waitcnt lgkmcnt(0)
	global_store_dword v[134:135], v32, off offset:588

; __device__ __forceinline__ unsigned pack2(float lo, float hi) { unsigned r; asm volatile("v_cvt_pk_bf16_f32 %0, %1, %2" : "=v"(r) : "v"(lo), "v"(hi)); return r; }
; template <int EPI>
; __device__ __forceinline__ void gemm_phase(const GemmDesc d, u16* shm, unsigned sx, unsigned srank, unsigned snloc) {
;     ...
;               const float v0 = acc[ai][0][m][0][j] * rs0[0] + acc[ai][1][m][0][j] * rs1[0];
;               const float v1 = acc[ai][0][m][1][j] * rs0[1] + acc[ai][1][m][1][j] * rs1[1];
;               stg[(fq2 * 4 + j) * 36 + fr2] = v0; stg[(fq2 * 4 + j) * 36 + 16 + fr2] = v1;
;               if (pm == 0) {
;                 float a = (fr2 & 1) ? -(v0 + v1) : (v0 + v1);
;                 a += __shfl_xor(a, 1); a += __shfl_xor(a, 2); a += __shfl_xor(a, 4); a += __shfl_xor(a, 8);
;                 if (fr2 == 0) d.xs[((size_t)((pn & 15) * 4 + wc2)) * (NBATCH * DM) + (size_t)b * DM + z * 256 + ai * 128 + wr2 * 64 + m * 16 + fq2 * 4 + j] = a;
;               }
;             }
; #pragma unroll
;             for (int i = 0; i < 2; ++i) {
;               const int row_l = i * 8 + rl;
;               f32x4 v = *(const f32x4*)&stg[row_l * 36 + c4];
;               u32x2 w = {pack2(v[0], v[1]), pack2(v[2], v[3])};
;               *(u32x2*)(outp + (size_t)(ai * 128 + wr2 * 64 + m * 16 + row_l) * 4096) = w;
;             }
.LBB0_308:
	v_add_u32_e32 v36, 0x90, v132
	s_waitcnt lgkmcnt(0)
	ds_read_b128 v[32:35], v96
	s_waitcnt lgkmcnt(0)
	v_cvt_pk_bf16_f32 v32, v32, v33
	v_cvt_pk_bf16_f32 v33, v34, v35
	v_or_b32_e32 v34, v36, v114
	v_ashrrev_i32_e32 v35, 31, v34
	v_lshlrev_b64 v[34:35], 13, v[34:35]
	v_lshl_add_u64 v[34:35], v[112:113], 0, v[34:35]
	global_store_dwordx2 v[34:35], v[32:33], off
	ds_read_b128 v[32:35], v96 offset:1152
	s_waitcnt lgkmcnt(0)
	v_cvt_pk_bf16_f32 v32, v32, v33
	v_cvt_pk_bf16_f32 v33, v34, v35
	v_or_b32_e32 v34, v115, v36
	v_ashrrev_i32_e32 v35, 31, v34
	v_mul_f32_e32 v24, v24, v152
	v_lshlrev_b64 v[34:35], 13, v[34:35]
	v_fmac_f32_e32 v24, v20, v136
	v_mul_f32_e32 v20, v28, v151
	v_lshl_add_u64 v[34:35], v[112:113], 0, v[34:35]
	v_fmac_f32_e32 v20, v16, v137
	s_and_b64 vcc, exec, s[16:17]
	global_store_dwordx2 v[34:35], v[32:33], off
	ds_write_b32 v120, v24
	ds_write_b32 v116, v20 offset:64
	s_cbranch_vccnz .LBB0_312
	v_add_f32_e32 v16, v24, v20
	v_cndmask_b32_e64 v16, -v16, v16, s[14:15]
	s_nop 1
	v_add_f32_dpp v16, v16, v16 quad_perm:[1,0,3,2] row_mask:0xf bank_mask:0xf
	s_nop 1
	v_add_f32_dpp v16, v16, v16 quad_perm:[2,3,0,1] row_mask:0xf bank_mask:0xf
	s_nop 1
	v_add_f32_dpp v16, v16, v16 row_half_mirror row_mask:0xf bank_mask:0xf
	s_nop 1
	v_add_f32_dpp v16, v16, v16 row_mirror row_mask:0xf bank_mask:0xf
	s_and_saveexec_b64 s[4:5], s[12:13]
	s_cbranch_execz .LBB0_311
	s_waitcnt lgkmcnt(0)
	global_store_dword v[134:135], v16, off offset:640

; template <int EPI>
; __device__ __forceinline__ void gemm_phase(const GemmDesc d, u16* shm, unsigned sx, unsigned srank, unsigned snloc) {
;     ...
;             for (int j = 0; j < 4; ++j) {
;               const float v0 = acc[ai][0][m][0][j] * rs0[0] + acc[ai][1][m][0][j] * rs1[0];
;               const float v1 = acc[ai][0][m][1][j] * rs0[1] + acc[ai][1][m][1][j] * rs1[1];
;               stg[(fq2 * 4 + j) * 36 + fr2] = v0; stg[(fq2 * 4 + j) * 36 + 16 + fr2] = v1;
;               if (pm == 0) {
;                 float a = (fr2 & 1) ? -(v0 + v1) : (v0 + v1);
;                 a += __shfl_xor(a, 1); a += __shfl_xor(a, 2); a += __shfl_xor(a, 4); a += __shfl_xor(a, 8);
;                 if (fr2 == 0) d.xs[((size_t)((pn & 15) * 4 + wc2)) * (NBATCH * DM) + (size_t)b * DM + z * 256 + ai * 128 + wr2 * 64 + m * 16 + fq2 * 4 + j] = a;
;               }
.LBB0_312:
	v_mul_f32_e32 v16, v25, v152
	s_waitcnt lgkmcnt(0)
	v_mul_f32_e32 v20, v29, v151
	v_fmac_f32_e32 v16, v21, v136
	v_fmac_f32_e32 v20, v17, v137
	s_and_b64 vcc, exec, s[16:17]
	ds_write_b32 v120, v16 offset:144
	ds_write_b32 v116, v20 offset:208
	s_cbranch_vccnz .LBB0_316
	v_add_f32_e32 v16, v16, v20
	v_cndmask_b32_e64 v16, -v16, v16, s[14:15]
	s_nop 1
	v_add_f32_dpp v16, v16, v16 quad_perm:[1,0,3,2] row_mask:0xf bank_mask:0xf
	s_nop 1
	v_add_f32_dpp v16, v16, v16 quad_perm:[2,3,0,1] row_mask:0xf bank_mask:0xf
	s_nop 1
	v_add_f32_dpp v16, v16, v16 row_half_mirror row_mask:0xf bank_mask:0xf
	s_nop 1
	v_add_f32_dpp v16, v16, v16 row_mirror row_mask:0xf bank_mask:0xf
	s_and_saveexec_b64 s[4:5], s[12:13]
	s_cbranch_execz .LBB0_315
	s_waitcnt lgkmcnt(0)
	global_store_dword v[134:135], v16, off offset:644

; template <int EPI>
; __device__ __forceinline__ void gemm_phase(const GemmDesc d, u16* shm, unsigned sx, unsigned srank, unsigned snloc) {
;     ...
;             for (int j = 0; j < 4; ++j) {
;               const float v0 = acc[ai][0][m][0][j] * rs0[0] + acc[ai][1][m][0][j] * rs1[0];
;               const float v1 = acc[ai][0][m][1][j] * rs0[1] + acc[ai][1][m][1][j] * rs1[1];
;               stg[(fq2 * 4 + j) * 36 + fr2] = v0; stg[(fq2 * 4 + j) * 36 + 16 + fr2] = v1;
;               if (pm == 0) {
;                 float a = (fr2 & 1) ? -(v0 + v1) : (v0 + v1);
;                 a += __shfl_xor(a, 1); a += __shfl_xor(a, 2); a += __shfl_xor(a, 4); a += __shfl_xor(a, 8);
;                 if (fr2 == 0) d.xs[((size_t)((pn & 15) * 4 + wc2)) * (NBATCH * DM) + (size_t)b * DM + z * 256 + ai * 128 + wr2 * 64 + m * 16 + fq2 * 4 + j] = a;
;               }
.LBB0_316:
	v_mul_f32_e32 v16, v26, v152
	s_waitcnt lgkmcnt(0)
	v_mul_f32_e32 v17, v30, v151
	v_fmac_f32_e32 v16, v22, v136
	v_fmac_f32_e32 v17, v18, v137
	s_and_b64 vcc, exec, s[16:17]
	ds_write_b32 v120, v16 offset:288
	ds_write_b32 v116, v17 offset:352
	s_cbranch_vccnz .LBB0_320
	v_add_f32_e32 v16, v16, v17
	v_cndmask_b32_e64 v16, -v16, v16, s[14:15]
	s_nop 1
	v_add_f32_dpp v16, v16, v16 quad_perm:[1,0,3,2] row_mask:0xf bank_mask:0xf
	s_nop 1
	v_add_f32_dpp v16, v16, v16 quad_perm:[2,3,0,1] row_mask:0xf bank_mask:0xf
	s_nop 1
	v_add_f32_dpp v16, v16, v16 row_half_mirror row_mask:0xf bank_mask:0xf
	s_nop 1
	v_add_f32_dpp v16, v16, v16 row_mirror row_mask:0xf bank_mask:0xf
	s_and_saveexec_b64 s[4:5], s[12:13]
	s_cbranch_execz .LBB0_319
	s_waitcnt lgkmcnt(0)
	global_store_dword v[134:135], v16, off offset:648

; template <int EPI>
; __device__ __forceinline__ void gemm_phase(const GemmDesc d, u16* shm, unsigned sx, unsigned srank, unsigned snloc) {
;     ...
;             for (int j = 0; j < 4; ++j) {
;               const float v0 = acc[ai][0][m][0][j] * rs0[0] + acc[ai][1][m][0][j] * rs1[0];
;               const float v1 = acc[ai][0][m][1][j] * rs0[1] + acc[ai][1][m][1][j] * rs1[1];
;               stg[(fq2 * 4 + j) * 36 + fr2] = v0; stg[(fq2 * 4 + j) * 36 + 16 + fr2] = v1;
;               if (pm == 0) {
;                 float a = (fr2 & 1) ? -(v0 + v1) : (v0 + v1);
;                 a += __shfl_xor(a, 1); a += __shfl_xor(a, 2); a += __shfl_xor(a, 4); a += __shfl_xor(a, 8);
;                 if (fr2 == 0) d.xs[((size_t)((pn & 15) * 4 + wc2)) * (NBATCH * DM) + (size_t)b * DM + z * 256 + ai * 128 + wr2 * 64 + m * 16 + fq2 * 4 + j] = a;
;               }
.LBB0_320:
	v_mul_f32_e32 v16, v27, v152
	s_waitcnt lgkmcnt(0)
	v_mul_f32_e32 v17, v31, v151
	v_fmac_f32_e32 v16, v23, v136
	v_fmac_f32_e32 v17, v19, v137
	s_and_b64 vcc, exec, s[16:17]
	ds_write_b32 v120, v16 offset:432
	ds_write_b32 v116, v17 offset:496
	s_cbranch_vccnz .LBB0_324
	v_add_f32_e32 v16, v16, v17
	v_cndmask_b32_e64 v16, -v16, v16, s[14:15]
	s_nop 1
	v_add_f32_dpp v16, v16, v16 quad_perm:[1,0,3,2] row_mask:0xf bank_mask:0xf
	s_nop 1
	v_add_f32_dpp v16, v16, v16 quad_perm:[2,3,0,1] row_mask:0xf bank_mask:0xf
	s_nop 1
	v_add_f32_dpp v16, v16, v16 row_half_mirror row_mask:0xf bank_mask:0xf
	s_nop 1
	v_add_f32_dpp v16, v16, v16 row_mirror row_mask:0xf bank_mask:0xf
	s_and_saveexec_b64 s[4:5], s[12:13]
	s_cbranch_execz .LBB0_323
	s_waitcnt lgkmcnt(0)
	global_store_dword v[134:135], v16, off offset:652

; __device__ __forceinline__ unsigned pack2(float lo, float hi) { unsigned r; asm volatile("v_cvt_pk_bf16_f32 %0, %1, %2" : "=v"(r) : "v"(lo), "v"(hi)); return r; }
; template <int EPI>
; __device__ __forceinline__ void gemm_phase(const GemmDesc d, u16* shm, unsigned sx, unsigned srank, unsigned snloc) {
;     ...
;               const float v0 = acc[ai][0][m][0][j] * rs0[0] + acc[ai][1][m][0][j] * rs1[0];
;               const float v1 = acc[ai][0][m][1][j] * rs0[1] + acc[ai][1][m][1][j] * rs1[1];
;               stg[(fq2 * 4 + j) * 36 + fr2] = v0; stg[(fq2 * 4 + j) * 36 + 16 + fr2] = v1;
;               if (pm == 0) {
;                 float a = (fr2 & 1) ? -(v0 + v1) : (v0 + v1);
;                 a += __shfl_xor(a, 1); a += __shfl_xor(a, 2); a += __shfl_xor(a, 4); a += __shfl_xor(a, 8);
;                 if (fr2 == 0) d.xs[((size_t)((pn & 15) * 4 + wc2)) * (NBATCH * DM) + (size_t)b * DM + z * 256 + ai * 128 + wr2 * 64 + m * 16 + fq2 * 4 + j] = a;
;               }
;             }
; #pragma unroll
;             for (int i = 0; i < 2; ++i) {
;               const int row_l = i * 8 + rl;
;               f32x4 v = *(const f32x4*)&stg[row_l * 36 + c4];
;               u32x2 w = {pack2(v[0], v[1]), pack2(v[2], v[3])};
;               *(u32x2*)(outp + (size_t)(ai * 128 + wr2 * 64 + m * 16 + row_l) * 4096) = w;
;             }
.LBB0_324:
	v_add_u32_e32 v20, 0xa0, v132
	s_waitcnt lgkmcnt(0)
	ds_read_b128 v[16:19], v96
	s_waitcnt lgkmcnt(0)
	v_cvt_pk_bf16_f32 v16, v16, v17
	v_cvt_pk_bf16_f32 v17, v18, v19
	v_or_b32_e32 v18, v20, v114
	v_ashrrev_i32_e32 v19, 31, v18
	v_lshlrev_b64 v[18:19], 13, v[18:19]
	v_lshl_add_u64 v[18:19], v[112:113], 0, v[18:19]
	global_store_dwordx2 v[18:19], v[16:17], off
	ds_read_b128 v[16:19], v96 offset:1152
	s_waitcnt lgkmcnt(0)
	v_cvt_pk_bf16_f32 v16, v16, v17
	v_cvt_pk_bf16_f32 v17, v18, v19
	v_or_b32_e32 v18, v115, v20
	v_ashrrev_i32_e32 v19, 31, v18
	v_mul_f32_e32 v8, v8, v152
	v_lshlrev_b64 v[18:19], 13, v[18:19]
	v_fmac_f32_e32 v8, v4, v136
	v_mul_f32_e32 v4, v12, v151
	v_lshl_add_u64 v[18:19], v[112:113], 0, v[18:19]
	v_fmac_f32_e32 v4, v0, v137
	s_and_b64 vcc, exec, s[16:17]
	global_store_dwordx2 v[18:19], v[16:17], off
	ds_write_b32 v120, v8
	ds_write_b32 v116, v4 offset:64
	s_cbranch_vccnz .LBB0_328
	v_add_f32_e32 v0, v8, v4
	v_cndmask_b32_e64 v0, -v0, v0, s[14:15]
	s_nop 1
	v_add_f32_dpp v0, v0, v0 quad_perm:[1,0,3,2] row_mask:0xf bank_mask:0xf
	s_nop 1
	v_add_f32_dpp v0, v0, v0 quad_perm:[2,3,0,1] row_mask:0xf bank_mask:0xf
	s_nop 1
	v_add_f32_dpp v0, v0, v0 row_half_mirror row_mask:0xf bank_mask:0xf
	s_nop 1
	v_add_f32_dpp v0, v0, v0 row_mirror row_mask:0xf bank_mask:0xf
	s_and_saveexec_b64 s[4:5], s[12:13]
	s_cbranch_execz .LBB0_327
	s_waitcnt lgkmcnt(0)
	global_store_dword v[134:135], v0, off offset:704

; template <int EPI>
; __device__ __forceinline__ void gemm_phase(const GemmDesc d, u16* shm, unsigned sx, unsigned srank, unsigned snloc) {
;     ...
;             for (int j = 0; j < 4; ++j) {
;               const float v0 = acc[ai][0][m][0][j] * rs0[0] + acc[ai][1][m][0][j] * rs1[0];
;               const float v1 = acc[ai][0][m][1][j] * rs0[1] + acc[ai][1][m][1][j] * rs1[1];
;               stg[(fq2 * 4 + j) * 36 + fr2] = v0; stg[(fq2 * 4 + j) * 36 + 16 + fr2] = v1;
;               if (pm == 0) {
;                 float a = (fr2 & 1) ? -(v0 + v1) : (v0 + v1);
;                 a += __shfl_xor(a, 1); a += __shfl_xor(a, 2); a += __shfl_xor(a, 4); a += __shfl_xor(a, 8);
;                 if (fr2 == 0) d.xs[((size_t)((pn & 15) * 4 + wc2)) * (NBATCH * DM) + (size_t)b * DM + z * 256 + ai * 128 + wr2 * 64 + m * 16 + fq2 * 4 + j] = a;
;               }
.LBB0_328:
	v_mul_f32_e32 v0, v9, v152
	s_waitcnt lgkmcnt(0)
	v_mul_f32_e32 v4, v13, v151
	v_fmac_f32_e32 v0, v5, v136
	v_fmac_f32_e32 v4, v1, v137
	s_and_b64 vcc, exec, s[16:17]
	ds_write_b32 v120, v0 offset:144
	ds_write_b32 v116, v4 offset:208
	s_cbranch_vccnz .LBB0_332
	v_add_f32_e32 v0, v0, v4
	v_cndmask_b32_e64 v0, -v0, v0, s[14:15]
	s_nop 1
	v_add_f32_dpp v0, v0, v0 quad_perm:[1,0,3,2] row_mask:0xf bank_mask:0xf
	s_nop 1
	v_add_f32_dpp v0, v0, v0 quad_perm:[2,3,0,1] row_mask:0xf bank_mask:0xf
	s_nop 1
	v_add_f32_dpp v0, v0, v0 row_half_mirror row_mask:0xf bank_mask:0xf
	s_nop 1
	v_add_f32_dpp v0, v0, v0 row_mirror row_mask:0xf bank_mask:0xf
	s_and_saveexec_b64 s[4:5], s[12:13]
	s_cbranch_execz .LBB0_331
	s_waitcnt lgkmcnt(0)
	global_store_dword v[134:135], v0, off offset:708

; template <int EPI>
; __device__ __forceinline__ void gemm_phase(const GemmDesc d, u16* shm, unsigned sx, unsigned srank, unsigned snloc) {
;     ...
;             for (int j = 0; j < 4; ++j) {
;               const float v0 = acc[ai][0][m][0][j] * rs0[0] + acc[ai][1][m][0][j] * rs1[0];
;               const float v1 = acc[ai][0][m][1][j] * rs0[1] + acc[ai][1][m][1][j] * rs1[1];
;               stg[(fq2 * 4 + j) * 36 + fr2] = v0; stg[(fq2 * 4 + j) * 36 + 16 + fr2] = v1;
;               if (pm == 0) {
;                 float a = (fr2 & 1) ? -(v0 + v1) : (v0 + v1);
;                 a += __shfl_xor(a, 1); a += __shfl_xor(a, 2); a += __shfl_xor(a, 4); a += __shfl_xor(a, 8);
;                 if (fr2 == 0) d.xs[((size_t)((pn & 15) * 4 + wc2)) * (NBATCH * DM) + (size_t)b * DM + z * 256 + ai * 128 + wr2 * 64 + m * 16 + fq2 * 4 + j] = a;
;               }
.LBB0_332:
	v_mul_f32_e32 v0, v10, v152
	s_waitcnt lgkmcnt(0)
	v_mul_f32_e32 v1, v14, v151
	v_fmac_f32_e32 v0, v6, v136
	v_fmac_f32_e32 v1, v2, v137
	s_and_b64 vcc, exec, s[16:17]
	ds_write_b32 v120, v0 offset:288
	ds_write_b32 v116, v1 offset:352
	s_cbranch_vccnz .LBB0_336
	v_add_f32_e32 v0, v0, v1
	v_cndmask_b32_e64 v0, -v0, v0, s[14:15]
	s_nop 1
	v_add_f32_dpp v0, v0, v0 quad_perm:[1,0,3,2] row_mask:0xf bank_mask:0xf
	s_nop 1
	v_add_f32_dpp v0, v0, v0 quad_perm:[2,3,0,1] row_mask:0xf bank_mask:0xf
	s_nop 1
	v_add_f32_dpp v0, v0, v0 row_half_mirror row_mask:0xf bank_mask:0xf
	s_nop 1
	v_add_f32_dpp v0, v0, v0 row_mirror row_mask:0xf bank_mask:0xf
	s_and_saveexec_b64 s[4:5], s[12:13]
	s_cbranch_execz .LBB0_335
	s_waitcnt lgkmcnt(0)
	global_store_dword v[134:135], v0, off offset:712

; template <int EPI>
; __device__ __forceinline__ void gemm_phase(const GemmDesc d, u16* shm, unsigned sx, unsigned srank, unsigned snloc) {
;     ...
;             for (int j = 0; j < 4; ++j) {
;               const float v0 = acc[ai][0][m][0][j] * rs0[0] + acc[ai][1][m][0][j] * rs1[0];
;               const float v1 = acc[ai][0][m][1][j] * rs0[1] + acc[ai][1][m][1][j] * rs1[1];
;               stg[(fq2 * 4 + j) * 36 + fr2] = v0; stg[(fq2 * 4 + j) * 36 + 16 + fr2] = v1;
;               if (pm == 0) {
;                 float a = (fr2 & 1) ? -(v0 + v1) : (v0 + v1);
;                 a += __shfl_xor(a, 1); a += __shfl_xor(a, 2); a += __shfl_xor(a, 4); a += __shfl_xor(a, 8);
;                 if (fr2 == 0) d.xs[((size_t)((pn & 15) * 4 + wc2)) * (NBATCH * DM) + (size_t)b * DM + z * 256 + ai * 128 + wr2 * 64 + m * 16 + fq2 * 4 + j] = a;
;               }
.LBB0_336:
	v_mul_f32_e32 v0, v11, v152
	s_waitcnt lgkmcnt(0)
	v_mul_f32_e32 v1, v15, v151
	v_fmac_f32_e32 v0, v7, v136
	v_fmac_f32_e32 v1, v3, v137
	s_and_b64 vcc, exec, s[16:17]
	ds_write_b32 v120, v0 offset:432
	ds_write_b32 v116, v1 offset:496
	s_cbranch_vccnz .LBB0_340
	v_add_f32_e32 v0, v0, v1
	v_cndmask_b32_e64 v0, -v0, v0, s[14:15]
	s_nop 1
	v_add_f32_dpp v0, v0, v0 quad_perm:[1,0,3,2] row_mask:0xf bank_mask:0xf
	s_nop 1
	v_add_f32_dpp v0, v0, v0 quad_perm:[2,3,0,1] row_mask:0xf bank_mask:0xf
	s_nop 1
	v_add_f32_dpp v0, v0, v0 row_half_mirror row_mask:0xf bank_mask:0xf
	s_nop 1
	v_add_f32_dpp v0, v0, v0 row_mirror row_mask:0xf bank_mask:0xf
	s_and_saveexec_b64 s[4:5], s[12:13]
	s_cbranch_execz .LBB0_339
	s_waitcnt lgkmcnt(0)
	global_store_dword v[134:135], v0, off offset:716
